# norm2 pass context-row path first half: gate vectors of groups 2,3 and residual of group 3 loaded right after group 0's store together with group 1's
# speedup vs baseline: 1.0014x; 1.0014x over previous
; __device__ __forceinline__ void norm_mod_pass(const float* xlat, float* xctx, const float* gvec, const float* modL, int ch_sh, int ch_sc, bf16* H, int nrows, int gw, int NGW, int lane, const bf16* x1a, const bf16* x1b, const float* P, int nsplit, const float* pgate) {
;     ...
;         for (int r = TLAT + gw; r < nrows; r += NGW) {
;             f32x4 v[4], pp_[4][11];
; #pragma unroll
;             for (int jj = 0; jj < 4; ++jj) { const int cidx = 4 * lane + 256 * jj; v[jj] = *(const f32x4*)(xctx + (size_t)(r - TLAT) * DM + cidx);
; #pragma unroll
;                 for (int s = 0; s < 11; ++s) { const int se = s < nsplit ? s : nsplit - 1; pp_[jj][s] = *(const f32x4*)(P + ((size_t)se * TCTX + (r - TLAT)) * DM + cidx); } }
;             float ss = 0.f;
; #pragma unroll
;             for (int jj = 0; jj < 4; ++jj) { const int cidx = 4 * lane + 256 * jj; f32x4 a = (f32x4){0.f, 0.f, 0.f, 0.f};
; #pragma unroll
;                 for (int s = 0; s < 11; ++s) a += pp_[jj][s] * (s < nsplit ? 1.f : 0.f);
;                 v[jj] += *(const f32x4*)(pgate + cidx) * a; *(f32x4*)(xctx + (size_t)(r - TLAT) * DM + cidx) = v[jj];
;                 ss += (v[jj].x * v[jj].x + v[jj].y * v[jj].y) + (v[jj].z * v[jj].z + v[jj].w * v[jj].w); }
.LBB0_60:
	v_lshl_add_u64 v[8:9], s[30:31], 0, v[80:81]
	v_lshl_add_u64 v[94:95], s[30:31], 0, v[76:77]
	v_lshl_add_u64 v[10:11], s[30:31], 0, v[82:83]
	v_lshl_add_u64 v[20:21], s[30:31], 0, v[84:85]
	v_lshl_add_u64 v[24:25], s[30:31], 0, v[88:89]
	v_lshl_add_u64 v[28:29], s[30:31], 0, v[90:91]
	v_lshl_add_u64 v[32:33], s[30:31], 0, v[92:93]
	v_lshl_add_u64 v[36:37], s[30:31], 0, v[86:87]
	v_lshl_add_u64 v[192:193], s[30:31], 0, v[78:79]
	global_load_dwordx4 v[0:3], v[8:9], off offset:-2048
	global_load_dwordx4 v[4:7], v[10:11], off offset:-2048
	global_load_dwordx4 v[40:43], v[20:21], off offset:-2048
	global_load_dwordx4 v[96:99], v[24:25], off offset:-2048
	global_load_dwordx4 v[100:103], v[28:29], off offset:-2048
	global_load_dwordx4 v[104:107], v[32:33], off offset:-2048
	global_load_dwordx4 v[108:111], v[36:37], off offset:-2048
	global_load_dwordx4 v[112:115], v[192:193], off offset:-2048
	global_load_dwordx4 v[116:119], v[94:95], off
	global_load_dwordx4 v[120:123], v[50:51], off
	v_mov_b32_e32 v47, v46
	global_load_dwordx4 v[124:127], v[94:95], off offset:1024
	global_load_dwordx4 v[128:131], v[8:9], off offset:-1024
	global_load_dwordx4 v[132:135], v[10:11], off offset:-1024
	global_load_dwordx4 v[136:139], v[20:21], off offset:-1024
	global_load_dwordx4 v[140:143], v[24:25], off offset:-1024
	global_load_dwordx4 v[144:147], v[28:29], off offset:-1024
	global_load_dwordx4 v[148:151], v[32:33], off offset:-1024
	global_load_dwordx4 v[152:155], v[36:37], off offset:-1024
	global_load_dwordx4 v[156:159], v[192:193], off offset:-1024
	global_load_dwordx4 v[160:163], v[8:9], off
	global_load_dwordx4 v[12:15], v[8:9], off offset:1024
	global_load_dwordx4 v[164:167], v[10:11], off
	global_load_dwordx4 v[16:19], v[10:11], off offset:1024
	global_load_dwordx4 v[168:171], v[20:21], off
	s_nop 0
	global_load_dwordx4 v[20:23], v[20:21], off offset:1024
	s_nop 0
	global_load_dwordx4 v[172:175], v[24:25], off
	s_nop 0
	global_load_dwordx4 v[24:27], v[24:25], off offset:1024
	s_nop 0
	global_load_dwordx4 v[176:179], v[28:29], off
	s_nop 0
	global_load_dwordx4 v[28:31], v[28:29], off offset:1024
	s_nop 0
	global_load_dwordx4 v[180:183], v[32:33], off
	s_nop 0
	global_load_dwordx4 v[32:35], v[32:33], off offset:1024
	s_nop 0
	global_load_dwordx4 v[184:187], v[36:37], off
	s_nop 0
	global_load_dwordx4 v[36:39], v[36:37], off offset:1024
	s_nop 0
	global_load_dwordx4 v[188:191], v[192:193], off
	global_load_dwordx4 v[8:11], v[192:193], off offset:1024
	s_add_i32 s8, s8, s60
	v_lshl_add_u64 v[76:77], v[76:77], 0, s[12:13]
	v_lshl_add_u64 v[78:79], v[78:79], 0, s[12:13]
	v_lshl_add_u64 v[80:81], v[80:81], 0, s[12:13]
	v_lshl_add_u64 v[82:83], v[82:83], 0, s[12:13]
	v_lshl_add_u64 v[84:85], v[84:85], 0, s[12:13]
	v_lshl_add_u64 v[86:87], v[86:87], 0, s[12:13]
	v_lshl_add_u64 v[88:89], v[88:89], 0, s[12:13]
	v_lshl_add_u64 v[90:91], v[90:91], 0, s[12:13]
	v_lshl_add_u64 v[92:93], v[92:93], 0, s[12:13]
	s_waitcnt vmcnt(0)
	v_pk_fma_f32 v[14:15], v[46:47], v[14:15], 0 op_sel_hi:[1,1,0]
	v_pk_fma_f32 v[12:13], v[48:49], v[12:13], 0 op_sel_hi:[1,1,0]
	s_waitcnt vmcnt(12)
	v_pk_fma_f32 v[14:15], v[46:47], v[18:19], v[14:15]
	v_pk_fma_f32 v[2:3], v[46:47], v[2:3], 0 op_sel_hi:[1,1,0]
	v_pk_fma_f32 v[0:1], v[48:49], v[0:1], 0 op_sel_hi:[1,1,0]
	v_pk_fma_f32 v[2:3], v[46:47], v[6:7], v[2:3]
	v_pk_fma_f32 v[0:1], v[48:49], v[4:5], v[0:1]
	v_pk_fma_f32 v[2:3], v[46:47], v[42:43], v[2:3]
	v_pk_fma_f32 v[0:1], v[48:49], v[40:41], v[0:1]
	v_pk_fma_f32 v[2:3], v[46:47], v[98:99], v[2:3]
	v_pk_fma_f32 v[0:1], v[48:49], v[96:97], v[0:1]
	v_pk_fma_f32 v[2:3], v[46:47], v[102:103], v[2:3]
	v_pk_fma_f32 v[0:1], v[48:49], v[100:101], v[0:1]
	v_pk_fma_f32 v[2:3], v[46:47], v[106:107], v[2:3]
	v_pk_fma_f32 v[0:1], v[48:49], v[104:105], v[0:1]
	v_pk_fma_f32 v[2:3], v[46:47], v[110:111], v[2:3]
	v_pk_fma_f32 v[0:1], v[48:49], v[108:109], v[0:1]
	v_pk_fma_f32 v[2:3], v[46:47], v[114:115], v[2:3]
	v_pk_fma_f32 v[0:1], v[48:49], v[112:113], v[0:1]
	v_pk_fma_f32 v[2:3], v[114:115], 0, v[2:3] op_sel_hi:[1,0,1]
	v_pk_fma_f32 v[0:1], v[112:113], 0, v[0:1] op_sel_hi:[1,0,1]
	v_pk_fma_f32 v[2:3], v[114:115], 0, v[2:3] op_sel_hi:[1,0,1]
	v_pk_fma_f32 v[0:1], v[112:113], 0, v[0:1] op_sel_hi:[1,0,1]
	v_pk_fma_f32 v[2:3], v[114:115], 0, v[2:3] op_sel_hi:[1,0,1]
	v_pk_fma_f32 v[0:1], v[112:113], 0, v[0:1] op_sel_hi:[1,0,1]
	v_pk_fma_f32 v[2:3], v[2:3], v[122:123], v[118:119]
	v_pk_fma_f32 v[0:1], v[0:1], v[120:121], v[116:117]
	global_store_dwordx4 v[94:95], v[0:3], off
	global_load_dwordx4 v[4:7], v[52:53], off
	global_load_dwordx4 v[40:43], v[94:95], off offset:2048
	global_load_dwordx4 v[212:215], v[54:55], off
	global_load_dwordx4 v[216:219], v[94:95], off offset:3072
	global_load_dwordx4 v[220:223], v[56:57], off
	v_pk_fma_f32 v[96:97], v[46:47], v[130:131], 0 op_sel_hi:[1,1,0]
	v_pk_fma_f32 v[98:99], v[48:49], v[128:129], 0 op_sel_hi:[1,1,0]
	v_pk_fma_f32 v[96:97], v[46:47], v[134:135], v[96:97]
	v_pk_fma_f32 v[98:99], v[48:49], v[132:133], v[98:99]
	v_pk_fma_f32 v[96:97], v[46:47], v[138:139], v[96:97]
	v_pk_fma_f32 v[98:99], v[48:49], v[136:137], v[98:99]
	v_pk_fma_f32 v[96:97], v[46:47], v[142:143], v[96:97]
	v_pk_fma_f32 v[98:99], v[48:49], v[140:141], v[98:99]
	v_pk_fma_f32 v[96:97], v[46:47], v[146:147], v[96:97]
	v_pk_fma_f32 v[98:99], v[48:49], v[144:145], v[98:99]
	v_pk_fma_f32 v[96:97], v[46:47], v[150:151], v[96:97]
	v_pk_fma_f32 v[98:99], v[48:49], v[148:149], v[98:99]
	v_pk_fma_f32 v[96:97], v[46:47], v[154:155], v[96:97]
	v_pk_fma_f32 v[98:99], v[48:49], v[152:153], v[98:99]
	v_pk_fma_f32 v[96:97], v[46:47], v[158:159], v[96:97]
	v_pk_fma_f32 v[98:99], v[48:49], v[156:157], v[98:99]
	v_pk_fma_f32 v[96:97], v[158:159], 0, v[96:97] op_sel_hi:[1,0,1]
	v_pk_fma_f32 v[98:99], v[156:157], 0, v[98:99] op_sel_hi:[1,0,1]
	v_pk_fma_f32 v[96:97], v[158:159], 0, v[96:97] op_sel_hi:[1,0,1]
	v_pk_fma_f32 v[98:99], v[156:157], 0, v[98:99] op_sel_hi:[1,0,1]
	v_pk_fma_f32 v[96:97], v[158:159], 0, v[96:97] op_sel_hi:[1,0,1]
	v_pk_fma_f32 v[98:99], v[156:157], 0, v[98:99] op_sel_hi:[1,0,1]
	v_pk_fma_f32 v[104:105], v[46:47], v[162:163], 0 op_sel_hi:[1,1,0]
	v_pk_fma_f32 v[106:107], v[48:49], v[160:161], 0 op_sel_hi:[1,1,0]
	v_pk_fma_f32 v[104:105], v[46:47], v[166:167], v[104:105]
	v_pk_fma_f32 v[106:107], v[48:49], v[164:165], v[106:107]
	s_waitcnt vmcnt(17)
; __device__ __forceinline__ void norm_mod_pass(const float* xlat, float* xctx, const float* gvec, const float* modL, int ch_sh, int ch_sc, bf16* H, int nrows, int gw, int NGW, int lane, const bf16* x1a, const bf16* x1b, const float* P, int nsplit, const float* pgate) {
;     ...
;             for (int jj = 0; jj < 4; ++jj) { const int cidx = 4 * lane + 256 * jj; f32x4 a = (f32x4){0.f, 0.f, 0.f, 0.f};
; #pragma unroll
;                 for (int s = 0; s < 11; ++s) a += pp_[jj][s] * (s < nsplit ? 1.f : 0.f);
;                 v[jj] += *(const f32x4*)(pgate + cidx) * a; *(f32x4*)(xctx + (size_t)(r - TLAT) * DM + cidx) = v[jj];
;                 ss += (v[jj].x * v[jj].x + v[jj].y * v[jj].y) + (v[jj].z * v[jj].z + v[jj].w * v[jj].w); }
;             ss = wave_sum(ss); const float rs = 1.0f / sqrtf(ss * (1.0f / DM) + EPSN);
; #pragma unroll
;             for (int jj = 0; jj < 4; ++jj) { const int cidx = 4 * lane + 256 * jj; const f32x4 gmv = *(const f32x4*)(gvec + cidx) * (*(const f32x4*)(sc + cidx) + 1.0f);
;                 const f32x4 o = v[jj] * rs * gmv + *(const f32x4*)(sh + cidx); v2u w; w.x = pk2(o.x, o.y); w.y = pk2(o.z, o.w);
;                 *(v2u*)(H + (size_t)r * DM + cidx) = w; }
	v_pk_fma_f32 v[104:105], v[46:47], v[170:171], v[104:105]
	v_pk_fma_f32 v[106:107], v[48:49], v[168:169], v[106:107]
	s_waitcnt vmcnt(15)
	v_pk_fma_f32 v[104:105], v[46:47], v[174:175], v[104:105]
	v_pk_fma_f32 v[106:107], v[48:49], v[172:173], v[106:107]
	s_waitcnt vmcnt(13)
	v_pk_fma_f32 v[104:105], v[46:47], v[178:179], v[104:105]
	v_pk_fma_f32 v[106:107], v[48:49], v[176:177], v[106:107]
	s_waitcnt vmcnt(11)
	v_pk_fma_f32 v[104:105], v[46:47], v[182:183], v[104:105]
	v_pk_fma_f32 v[106:107], v[48:49], v[180:181], v[106:107]
	s_waitcnt vmcnt(9)
	v_pk_fma_f32 v[104:105], v[46:47], v[186:187], v[104:105]
	v_pk_fma_f32 v[106:107], v[48:49], v[184:185], v[106:107]
	s_waitcnt vmcnt(7)
	v_pk_fma_f32 v[104:105], v[46:47], v[190:191], v[104:105]
	v_pk_fma_f32 v[106:107], v[48:49], v[188:189], v[106:107]
	v_pk_fma_f32 v[104:105], v[190:191], 0, v[104:105] op_sel_hi:[1,0,1]
	v_pk_fma_f32 v[106:107], v[188:189], 0, v[106:107] op_sel_hi:[1,0,1]
	v_pk_fma_f32 v[104:105], v[190:191], 0, v[104:105] op_sel_hi:[1,0,1]
	v_pk_fma_f32 v[106:107], v[188:189], 0, v[106:107] op_sel_hi:[1,0,1]
	v_pk_fma_f32 v[104:105], v[190:191], 0, v[104:105] op_sel_hi:[1,0,1]
	v_pk_fma_f32 v[106:107], v[188:189], 0, v[106:107] op_sel_hi:[1,0,1]
	v_pk_fma_f32 v[12:13], v[48:49], v[16:17], v[12:13]
	v_pk_fma_f32 v[14:15], v[46:47], v[22:23], v[14:15]
	v_pk_fma_f32 v[12:13], v[48:49], v[20:21], v[12:13]
	v_pk_fma_f32 v[14:15], v[46:47], v[26:27], v[14:15]
	v_pk_fma_f32 v[12:13], v[48:49], v[24:25], v[12:13]
	v_pk_fma_f32 v[14:15], v[46:47], v[30:31], v[14:15]
	v_pk_fma_f32 v[12:13], v[48:49], v[28:29], v[12:13]
	v_pk_fma_f32 v[14:15], v[46:47], v[34:35], v[14:15]
	v_pk_fma_f32 v[12:13], v[48:49], v[32:33], v[12:13]
	v_pk_fma_f32 v[14:15], v[46:47], v[38:39], v[14:15]
	v_pk_fma_f32 v[12:13], v[48:49], v[36:37], v[12:13]
	s_waitcnt vmcnt(6)
	v_pk_fma_f32 v[14:15], v[46:47], v[10:11], v[14:15]
	v_pk_fma_f32 v[12:13], v[48:49], v[8:9], v[12:13]
	v_pk_fma_f32 v[14:15], v[10:11], 0, v[14:15] op_sel_hi:[1,0,1]
	v_pk_fma_f32 v[12:13], v[8:9], 0, v[12:13] op_sel_hi:[1,0,1]
	v_pk_fma_f32 v[14:15], v[10:11], 0, v[14:15] op_sel_hi:[1,0,1]
	v_pk_fma_f32 v[12:13], v[8:9], 0, v[12:13] op_sel_hi:[1,0,1]
	v_pk_fma_f32 v[10:11], v[10:11], 0, v[14:15] op_sel_hi:[1,0,1]
	v_pk_fma_f32 v[8:9], v[8:9], 0, v[12:13] op_sel_hi:[1,0,1]
	v_pk_mul_f32 v[12:13], v[2:3], v[2:3]
	v_pk_mul_f32 v[14:15], v[0:1], v[0:1]
	s_waitcnt vmcnt(4)
	v_pk_fma_f32 v[6:7], v[96:97], v[6:7], v[126:127]
	v_pk_fma_f32 v[4:5], v[98:99], v[4:5], v[124:125]
	global_store_dwordx4 v[94:95], v[4:7], off offset:1024
	v_pk_mov_b32 v[16:17], v[14:15], v[12:13] op_sel:[1,0]
	v_mov_b32_e32 v15, v13
	v_pk_add_f32 v[12:13], v[14:15], v[16:17]
	v_pk_mul_f32 v[14:15], v[4:5], v[4:5]
	v_pk_add_f32 v[24:25], v[12:13], v[12:13] op_sel:[0,1] op_sel_hi:[1,0]
	v_pk_mul_f32 v[12:13], v[6:7], v[6:7]
	s_waitcnt vmcnt(2)
	v_pk_fma_f32 v[42:43], v[104:105], v[214:215], v[42:43]
	v_pk_fma_f32 v[40:41], v[106:107], v[212:213], v[40:41]
	global_store_dwordx4 v[94:95], v[40:43], off offset:2048
	v_pk_mov_b32 v[16:17], v[14:15], v[12:13] op_sel:[1,0]
	v_mov_b32_e32 v15, v13
	v_pk_add_f32 v[12:13], v[14:15], v[16:17]
	v_mul_f32_e32 v14, v43, v43
	v_pk_add_f32 v[26:27], v[12:13], v[12:13] op_sel:[0,1] op_sel_hi:[1,0]
	v_mul_f32_e32 v12, v41, v41
	v_pk_fma_f32 v[28:29], v[40:41], v[40:41], v[12:13] op_sel_hi:[1,1,0]
	v_pk_fma_f32 v[30:31], v[42:43], v[42:43], v[14:15] op_sel_hi:[1,1,0]
	v_lshl_add_u64 v[104:105], s[30:31], 0, v[74:75]
	v_add_co_u32_e32 v104, vcc, s72, v104
	v_lshl_add_u64 v[74:75], v[74:75], 0, s[10:11]
	s_nop 0
	v_addc_co_u32_e32 v105, vcc, 0, v105, vcc
	s_waitcnt vmcnt(0)
	v_pk_fma_f32 v[10:11], v[10:11], v[222:223], v[218:219]
	v_pk_fma_f32 v[8:9], v[8:9], v[220:221], v[216:217]
	global_store_dwordx4 v[94:95], v[8:11], off offset:3072
	global_load_dwordx4 v[12:15], v[58:59], off
	global_load_dwordx4 v[16:19], v[44:45], off
	global_load_dwordx4 v[20:23], v[60:61], off
	global_load_dwordx4 v[128:131], v[62:63], off
	global_load_dwordx4 v[132:135], v[44:45], off offset:1024
	global_load_dwordx4 v[136:139], v[64:65], off
	global_load_dwordx4 v[140:143], v[66:67], off
	global_load_dwordx4 v[144:147], v[44:45], off offset:2048
	global_load_dwordx4 v[148:151], v[68:69], off
	global_load_dwordx4 v[152:155], v[70:71], off
	global_load_dwordx4 v[156:159], v[44:45], off offset:3072
	global_load_dwordx4 v[160:163], v[72:73], off
	v_mul_f32_e32 v25, v8, v8
	v_mul_f32_e32 v27, v9, v9
	v_mul_f32_e32 v31, v10, v10
	v_mul_f32_e32 v29, v11, v11
	v_pk_add_f32 v[24:25], v[24:25], v[26:27]
	v_pk_add_f32 v[26:27], v[28:29], v[30:31]
	s_waitcnt vmcnt(11)
; __device__ __forceinline__ void norm_mod_pass(const float* xlat, float* xctx, const float* gvec, const float* modL, int ch_sh, int ch_sc, bf16* H, int nrows, int gw, int NGW, int lane, const bf16* x1a, const bf16* x1b, const float* P, int nsplit, const float* pgate) {
;     ...
;             ss = wave_sum(ss); const float rs = 1.0f / sqrtf(ss * (1.0f / DM) + EPSN);
; #pragma unroll
;             for (int jj = 0; jj < 4; ++jj) { const int cidx = 4 * lane + 256 * jj; const f32x4 gmv = *(const f32x4*)(gvec + cidx) * (*(const f32x4*)(sc + cidx) + 1.0f);
;                 const f32x4 o = v[jj] * rs * gmv + *(const f32x4*)(sh + cidx); v2u w; w.x = pk2(o.x, o.y); w.y = pk2(o.z, o.w);
;                 *(v2u*)(H + (size_t)r * DM + cidx) = w; }
	v_pk_add_f32 v[14:15], v[14:15], 1.0 op_sel_hi:[1,0]
	v_pk_add_f32 v[24:25], v[24:25], v[26:27]
	v_pk_add_f32 v[12:13], v[12:13], 1.0 op_sel_hi:[1,0]
	v_add_f32_e32 v24, v24, v25
	s_waitcnt vmcnt(10)
	v_pk_mul_f32 v[14:15], v[18:19], v[14:15]
	v_pk_mul_f32 v[12:13], v[16:17], v[12:13]
	v_add_f32_dpp v24, v24, v24 quad_perm:[1,0,3,2] row_mask:0xf bank_mask:0xf bound_ctrl:1
	s_nop 1
	v_add_f32_dpp v24, v24, v24 quad_perm:[2,3,0,1] row_mask:0xf bank_mask:0xf bound_ctrl:1
	s_nop 1
	v_add_f32_dpp v24, v24, v24 row_half_mirror row_mask:0xf bank_mask:0xf bound_ctrl:1
	s_nop 1
	v_add_f32_dpp v24, v24, v24 row_mirror row_mask:0xf bank_mask:0xf bound_ctrl:1
	s_nop 0
	v_readlane_b32 s2, v24, 16
	v_readlane_b32 s3, v24, 48
	v_readlane_b32 s0, v24, 0
	v_readlane_b32 s1, v24, 32
	v_mov_b32_e32 v24, s2
	v_mov_b32_e32 v25, s3
	v_pk_add_f32 v[24:25], s[0:1], v[24:25]
	s_nop 0
	v_add_f32_e32 v24, v24, v25
	v_fmamk_f32 v24, v24, 0x3a800000, v243
	v_mul_f32_e32 v25, 0x4f800000, v24
	v_cmp_gt_f32_e32 vcc, s71, v24
	s_nop 1
	v_cndmask_b32_e32 v24, v24, v25, vcc
	v_sqrt_f32_e32 v25, v24
	s_nop 0
	v_add_u32_e32 v26, -1, v25
	v_add_u32_e32 v27, 1, v25
	v_fma_f32 v28, -v26, v25, v24
	v_fma_f32 v29, -v27, v25, v24
	v_cmp_ge_f32_e64 s[4:5], 0, v28
	s_nop 1
	v_cndmask_b32_e64 v25, v25, v26, s[4:5]
	v_cmp_lt_f32_e64 s[4:5], 0, v29
	s_nop 1
	v_cndmask_b32_e64 v25, v25, v27, s[4:5]
	v_mul_f32_e32 v26, 0x37800000, v25
	v_cndmask_b32_e32 v25, v25, v26, vcc
	v_cmp_class_f32_e32 vcc, v24, v244
	s_nop 1
	v_cndmask_b32_e32 v24, v25, v24, vcc
	v_div_scale_f32 v25, s[0:1], v24, v24, 1.0
	v_rcp_f32_e32 v27, v25
	v_div_scale_f32 v26, vcc, 1.0, v24, 1.0
	v_readlane_b32 s0, v254, 15
	v_fma_f32 v28, -v25, v27, 1.0
	v_fmac_f32_e32 v27, v28, v27
	v_mul_f32_e32 v28, v26, v27
	v_fma_f32 v29, -v25, v28, v26
	v_fmac_f32_e32 v28, v29, v27
	v_fma_f32 v25, -v25, v28, v26
	v_div_fmas_f32 v25, v25, v27, v28
	v_div_fixup_f32 v24, v25, v24, 1.0
	v_pk_mul_f32 v[0:1], v[0:1], v[24:25] op_sel_hi:[1,0]
	v_pk_mul_f32 v[2:3], v[2:3], v[24:25] op_sel_hi:[1,0]
	s_waitcnt vmcnt(9)
	v_pk_fma_f32 v[0:1], v[12:13], v[0:1], v[20:21]
	v_pk_fma_f32 v[2:3], v[14:15], v[2:3], v[22:23]
	v_cvt_pk_bf16_f32 v0, v0, v1
	v_cvt_pk_bf16_f32 v1, v2, v3
	global_store_dwordx2 v[104:105], v[0:1], off
	s_nop 0
	v_pk_mul_f32 v[4:5], v[4:5], v[24:25] op_sel_hi:[1,0]
	v_pk_mul_f32 v[6:7], v[6:7], v[24:25] op_sel_hi:[1,0]
	v_pk_mul_f32 v[8:9], v[8:9], v[24:25] op_sel_hi:[1,0]
	v_pk_mul_f32 v[10:11], v[10:11], v[24:25] op_sel_hi:[1,0]
	s_cmp_ge_i32 s8, s0
	s_waitcnt vmcnt(8)
	v_pk_add_f32 v[2:3], v[130:131], 1.0 op_sel_hi:[1,0]
	v_pk_add_f32 v[0:1], v[128:129], 1.0 op_sel_hi:[1,0]
	s_waitcnt vmcnt(7)
	v_pk_mul_f32 v[2:3], v[134:135], v[2:3]
	v_pk_mul_f32 v[0:1], v[132:133], v[0:1]
	s_waitcnt vmcnt(6)
	v_pk_fma_f32 v[2:3], v[2:3], v[6:7], v[138:139]
	v_pk_fma_f32 v[0:1], v[0:1], v[4:5], v[136:137]
	v_pk_mul_f32 v[16:17], v[40:41], v[24:25] op_sel_hi:[1,0]
	v_cvt_pk_bf16_f32 v0, v0, v1
	v_cvt_pk_bf16_f32 v1, v2, v3
	global_store_dwordx2 v[104:105], v[0:1], off offset:512
	s_nop 0
	v_pk_mul_f32 v[18:19], v[42:43], v[24:25] op_sel_hi:[1,0]
	s_waitcnt vmcnt(5)
	v_pk_add_f32 v[2:3], v[142:143], 1.0 op_sel_hi:[1,0]
	v_pk_add_f32 v[0:1], v[140:141], 1.0 op_sel_hi:[1,0]
	s_waitcnt vmcnt(4)
	v_pk_mul_f32 v[2:3], v[146:147], v[2:3]
	v_pk_mul_f32 v[0:1], v[144:145], v[0:1]
	s_waitcnt vmcnt(3)
	v_pk_fma_f32 v[2:3], v[18:19], v[2:3], v[150:151]
	v_pk_fma_f32 v[0:1], v[16:17], v[0:1], v[148:149]
	s_nop 0
	v_cvt_pk_bf16_f32 v0, v0, v1
	v_cvt_pk_bf16_f32 v1, v2, v3
	global_store_dwordx2 v[104:105], v[0:1], off offset:1024
	s_nop 0
	s_waitcnt vmcnt(2)
	v_pk_add_f32 v[2:3], v[154:155], 1.0 op_sel_hi:[1,0]
	v_pk_add_f32 v[0:1], v[152:153], 1.0 op_sel_hi:[1,0]
	s_waitcnt vmcnt(1)
	v_pk_mul_f32 v[2:3], v[158:159], v[2:3]
	v_pk_mul_f32 v[0:1], v[156:157], v[0:1]
	s_waitcnt vmcnt(0)
	v_pk_fma_f32 v[2:3], v[10:11], v[2:3], v[162:163]
	v_pk_fma_f32 v[0:1], v[8:9], v[0:1], v[160:161]
	s_nop 0
	v_cvt_pk_bf16_f32 v0, v0, v1
	v_cvt_pk_bf16_f32 v1, v2, v3
	global_store_dwordx2 v[104:105], v[0:1], off offset:1536
	s_cbranch_scc0 .LBB0_60
